# P1 K-loop segment heads: s_setprio 1 before the pre-MFMA barrier, redundant lgkmcnt(0) after it and no-op priority flip pairs deleted, half-unit test and out-of-line fourth MFMA block folded away
# speedup vs baseline: 1.0098x; 1.0098x over previous
.LBB0_105:
	s_waitcnt lgkmcnt(0)
	s_setprio 1
	s_barrier
	v_mfma_f32_16x16x32_bf16 v[38:41], v[150:153], v[190:193], v[38:41]
	v_mfma_f32_16x16x32_bf16 v[4:7], v[158:161], v[190:193], v[6:9]
	v_mfma_f32_16x16x32_bf16 v[50:53], v[150:153], v[182:185], v[50:53]
	v_mfma_f32_16x16x32_bf16 v[18:21], v[158:161], v[182:185], v[18:21]
	v_mfma_f32_16x16x32_bf16 v[46:49], v[150:153], v[174:177], v[46:49]
	v_mfma_f32_16x16x32_bf16 v[14:17], v[158:161], v[174:177], v[14:17]
	v_mfma_f32_16x16x32_bf16 v[42:45], v[150:153], v[166:169], v[42:45]
	v_mfma_f32_16x16x32_bf16 v[10:13], v[158:161], v[166:169], v[10:13]
	v_mfma_f32_16x16x32_bf16 v[38:41], v[154:157], v[194:197], v[38:41]
	v_mfma_f32_16x16x32_bf16 v[6:9], v[162:165], v[194:197], v[4:7]
	v_mfma_f32_16x16x32_bf16 v[50:53], v[154:157], v[186:189], v[50:53]
	v_mfma_f32_16x16x32_bf16 v[18:21], v[162:165], v[186:189], v[18:21]
	v_mfma_f32_16x16x32_bf16 v[46:49], v[154:157], v[178:181], v[46:49]
	v_mfma_f32_16x16x32_bf16 v[14:17], v[162:165], v[178:181], v[14:17]
	v_mfma_f32_16x16x32_bf16 v[42:45], v[154:157], v[170:173], v[42:45]
	v_mfma_f32_16x16x32_bf16 v[10:13], v[162:165], v[170:173], v[10:13]
	v_mfma_f32_16x16x32_bf16 v[62:65], v[134:137], v[190:193], v[62:65]
	v_mfma_f32_16x16x32_bf16 v[30:33], v[142:145], v[190:193], v[30:33]
	v_mfma_f32_16x16x32_bf16 v[66:69], v[134:137], v[182:185], v[66:69]
	v_mfma_f32_16x16x32_bf16 v[34:37], v[142:145], v[182:185], v[34:37]
	v_mfma_f32_16x16x32_bf16 v[58:61], v[134:137], v[174:177], v[58:61]
	v_mfma_f32_16x16x32_bf16 v[26:29], v[142:145], v[174:177], v[26:29]
	v_mfma_f32_16x16x32_bf16 v[54:57], v[134:137], v[166:169], v[54:57]
	v_mfma_f32_16x16x32_bf16 v[22:25], v[142:145], v[166:169], v[22:25]
	v_mfma_f32_16x16x32_bf16 v[62:65], v[138:141], v[194:197], v[62:65]
	v_mfma_f32_16x16x32_bf16 v[30:33], v[146:149], v[194:197], v[30:33]
	v_mfma_f32_16x16x32_bf16 v[66:69], v[138:141], v[186:189], v[66:69]
	v_mfma_f32_16x16x32_bf16 v[34:37], v[146:149], v[186:189], v[34:37]
	v_mfma_f32_16x16x32_bf16 v[58:61], v[138:141], v[178:181], v[58:61]
	v_mfma_f32_16x16x32_bf16 v[26:29], v[146:149], v[178:181], v[26:29]
	v_mfma_f32_16x16x32_bf16 v[54:57], v[138:141], v[170:173], v[54:57]
	v_mfma_f32_16x16x32_bf16 v[22:25], v[146:149], v[170:173], v[22:25]
	s_setprio 0

.LBB0_107:
	ds_read_b128 v[150:153], v248
	ds_read_b128 v[154:157], v248 offset:1024
	ds_read_b128 v[158:161], v248 offset:2048
	ds_read_b128 v[162:165], v248 offset:3072
	ds_read_b128 v[134:137], v249
	ds_read_b128 v[138:141], v249 offset:1024
	ds_read_b128 v[142:145], v249 offset:2048
	ds_read_b128 v[146:149], v249 offset:3072
	s_mov_b64 s[0:1], s[76:77]
	s_add_u32 s76, s0, 0x100
	s_addc_u32 s77, s1, 0
	s_cmp_lg_u32 s45, 12
	s_cselect_b64 s[88:89], -1, 0
	s_and_b64 s[2:3], s[88:89], exec
	s_cselect_b32 s3, s44, s63
	s_cselect_b32 s2, s36, s65
	s_cselect_b32 s85, s77, s4
	s_cselect_b32 s84, s76, s43
	v_lshl_add_u64 v[4:5], s[0:1], 0, v[214:215]
	s_add_i32 m0, s61, 0xc000
	s_waitcnt lgkmcnt(0)
	ds_read_b128 v[166:169], v250
	ds_read_b128 v[170:173], v250 offset:1024
	ds_read_b128 v[174:177], v250 offset:2048
	ds_read_b128 v[178:181], v250 offset:3072
	ds_read_b128 v[182:185], v250 offset:4096
	ds_read_b128 v[186:189], v250 offset:5120
	ds_read_b128 v[190:193], v250 offset:6144
	ds_read_b128 v[194:197], v250 offset:7168
	global_load_lds_dwordx4 v[4:5], off
	v_lshl_add_u64 v[4:5], s[0:1], 0, v[216:217]
	s_add_i32 m0, s61, 0xe000
	s_nop 0
	global_load_lds_dwordx4 v[4:5], off
	s_waitcnt vmcnt(8)
	s_waitcnt lgkmcnt(0)
	s_setprio 1
	s_barrier
	v_mfma_f32_16x16x32_bf16 v[102:105], v[150:153], v[166:169], v[102:105]
	v_mfma_f32_16x16x32_bf16 v[70:73], v[158:161], v[166:169], v[70:73]
	v_mfma_f32_16x16x32_bf16 v[114:117], v[150:153], v[174:177], v[114:117]
	v_mfma_f32_16x16x32_bf16 v[82:85], v[158:161], v[174:177], v[82:85]
	v_mfma_f32_16x16x32_bf16 v[110:113], v[150:153], v[182:185], v[110:113]
	v_mfma_f32_16x16x32_bf16 v[78:81], v[158:161], v[182:185], v[78:81]
	v_mfma_f32_16x16x32_bf16 v[106:109], v[150:153], v[190:193], v[106:109]
	v_mfma_f32_16x16x32_bf16 v[74:77], v[158:161], v[190:193], v[74:77]
	v_mfma_f32_16x16x32_bf16 v[102:105], v[154:157], v[170:173], v[102:105]
	v_mfma_f32_16x16x32_bf16 v[70:73], v[162:165], v[170:173], v[70:73]
	v_mfma_f32_16x16x32_bf16 v[114:117], v[154:157], v[178:181], v[114:117]
	v_mfma_f32_16x16x32_bf16 v[82:85], v[162:165], v[178:181], v[82:85]
	v_mfma_f32_16x16x32_bf16 v[110:113], v[154:157], v[186:189], v[110:113]
	v_mfma_f32_16x16x32_bf16 v[78:81], v[162:165], v[186:189], v[78:81]
	v_mfma_f32_16x16x32_bf16 v[106:109], v[154:157], v[194:197], v[106:109]
	v_mfma_f32_16x16x32_bf16 v[74:77], v[162:165], v[194:197], v[74:77]
	v_mfma_f32_16x16x32_bf16 v[130:133], v[134:137], v[166:169], v[130:133]
	v_mfma_f32_16x16x32_bf16 v[98:101], v[142:145], v[166:169], v[98:101]
	v_mfma_f32_16x16x32_bf16 v[126:129], v[134:137], v[174:177], v[126:129]
	v_mfma_f32_16x16x32_bf16 v[94:97], v[142:145], v[174:177], v[94:97]
	v_mfma_f32_16x16x32_bf16 v[122:125], v[134:137], v[182:185], v[122:125]
	v_mfma_f32_16x16x32_bf16 v[90:93], v[142:145], v[182:185], v[90:93]
	v_mfma_f32_16x16x32_bf16 v[118:121], v[134:137], v[190:193], v[118:121]
	v_mfma_f32_16x16x32_bf16 v[86:89], v[142:145], v[190:193], v[86:89]
	v_mfma_f32_16x16x32_bf16 v[130:133], v[138:141], v[170:173], v[130:133]
	v_mfma_f32_16x16x32_bf16 v[98:101], v[146:149], v[170:173], v[98:101]
	v_mfma_f32_16x16x32_bf16 v[126:129], v[138:141], v[178:181], v[126:129]
	v_mfma_f32_16x16x32_bf16 v[94:97], v[146:149], v[178:181], v[94:97]
	v_mfma_f32_16x16x32_bf16 v[122:125], v[138:141], v[186:189], v[122:125]
	v_mfma_f32_16x16x32_bf16 v[90:93], v[146:149], v[186:189], v[90:93]
	v_mfma_f32_16x16x32_bf16 v[118:121], v[138:141], v[194:197], v[118:121]
	v_mfma_f32_16x16x32_bf16 v[86:89], v[146:149], v[194:197], v[86:89]
	s_setprio 0
	s_barrier
	ds_read_b128 v[190:193], v250 offset:16384
	ds_read_b128 v[194:197], v250 offset:17408
	ds_read_b128 v[182:185], v250 offset:18432
	ds_read_b128 v[186:189], v250 offset:19456
	ds_read_b128 v[174:177], v250 offset:20480
	ds_read_b128 v[178:181], v250 offset:21504
	ds_read_b128 v[166:169], v250 offset:22528
	ds_read_b128 v[170:173], v250 offset:23552
	s_nor_b64 s[88:89], s[66:67], s[88:89]
	s_mov_b64 s[0:1], -1
	s_and_b64 vcc, exec, s[88:89]
	s_cbranch_vccz .LBB0_109
	s_waitcnt vmcnt(2)
	s_mov_b64 s[0:1], 0

.LBB0_111:
	v_cndmask_b32_e64 v3, 0, 1, s[86:87]
	v_cmp_ne_u32_e64 s[0:1], 1, v3
	s_waitcnt lgkmcnt(0)
	s_setprio 1
	s_barrier
	v_mfma_f32_16x16x32_bf16 v[38:41], v[150:153], v[190:193], v[38:41]
	v_mfma_f32_16x16x32_bf16 v[6:9], v[158:161], v[190:193], v[6:9]
	v_mfma_f32_16x16x32_bf16 v[50:53], v[150:153], v[182:185], v[50:53]
	v_mfma_f32_16x16x32_bf16 v[18:21], v[158:161], v[182:185], v[18:21]
	v_mfma_f32_16x16x32_bf16 v[46:49], v[150:153], v[174:177], v[46:49]
	v_mfma_f32_16x16x32_bf16 v[14:17], v[158:161], v[174:177], v[14:17]
	v_mfma_f32_16x16x32_bf16 v[42:45], v[150:153], v[166:169], v[42:45]
	v_mfma_f32_16x16x32_bf16 v[10:13], v[158:161], v[166:169], v[10:13]
	v_mfma_f32_16x16x32_bf16 v[38:41], v[154:157], v[194:197], v[38:41]
	v_mfma_f32_16x16x32_bf16 v[6:9], v[162:165], v[194:197], v[6:9]
	v_mfma_f32_16x16x32_bf16 v[50:53], v[154:157], v[186:189], v[50:53]
	v_mfma_f32_16x16x32_bf16 v[18:21], v[162:165], v[186:189], v[18:21]
	v_mfma_f32_16x16x32_bf16 v[46:49], v[154:157], v[178:181], v[46:49]
	v_mfma_f32_16x16x32_bf16 v[14:17], v[162:165], v[178:181], v[14:17]
	v_mfma_f32_16x16x32_bf16 v[42:45], v[154:157], v[170:173], v[42:45]
	v_mfma_f32_16x16x32_bf16 v[10:13], v[162:165], v[170:173], v[10:13]
	v_mfma_f32_16x16x32_bf16 v[62:65], v[134:137], v[190:193], v[62:65]
	v_mfma_f32_16x16x32_bf16 v[30:33], v[142:145], v[190:193], v[30:33]
	v_mfma_f32_16x16x32_bf16 v[66:69], v[134:137], v[182:185], v[66:69]
	v_mfma_f32_16x16x32_bf16 v[34:37], v[142:145], v[182:185], v[34:37]
	v_mfma_f32_16x16x32_bf16 v[58:61], v[134:137], v[174:177], v[58:61]
	v_mfma_f32_16x16x32_bf16 v[26:29], v[142:145], v[174:177], v[26:29]
	v_mfma_f32_16x16x32_bf16 v[54:57], v[134:137], v[166:169], v[54:57]
	v_mfma_f32_16x16x32_bf16 v[22:25], v[142:145], v[166:169], v[22:25]
	v_mfma_f32_16x16x32_bf16 v[62:65], v[138:141], v[194:197], v[62:65]
	v_mfma_f32_16x16x32_bf16 v[30:33], v[146:149], v[194:197], v[30:33]
	v_mfma_f32_16x16x32_bf16 v[66:69], v[138:141], v[186:189], v[66:69]
	v_mfma_f32_16x16x32_bf16 v[34:37], v[146:149], v[186:189], v[34:37]
	v_mfma_f32_16x16x32_bf16 v[58:61], v[138:141], v[178:181], v[58:61]
	v_mfma_f32_16x16x32_bf16 v[26:29], v[146:149], v[178:181], v[26:29]
	v_mfma_f32_16x16x32_bf16 v[54:57], v[138:141], v[170:173], v[54:57]
	v_mfma_f32_16x16x32_bf16 v[22:25], v[146:149], v[170:173], v[22:25]
	s_setprio 0

.LBB0_117:
	s_waitcnt lgkmcnt(0)
	s_setprio 1
	s_barrier
	v_mfma_f32_16x16x32_bf16 v[102:105], v[150:153], v[190:193], v[102:105]
	v_mfma_f32_16x16x32_bf16 v[70:73], v[158:161], v[190:193], v[70:73]
	v_mfma_f32_16x16x32_bf16 v[114:117], v[150:153], v[182:185], v[114:117]
	v_mfma_f32_16x16x32_bf16 v[82:85], v[158:161], v[182:185], v[82:85]
	v_mfma_f32_16x16x32_bf16 v[110:113], v[150:153], v[174:177], v[110:113]
	v_mfma_f32_16x16x32_bf16 v[78:81], v[158:161], v[174:177], v[78:81]
	v_mfma_f32_16x16x32_bf16 v[106:109], v[150:153], v[166:169], v[106:109]
	v_mfma_f32_16x16x32_bf16 v[74:77], v[158:161], v[166:169], v[74:77]
	v_mfma_f32_16x16x32_bf16 v[102:105], v[154:157], v[194:197], v[102:105]
	v_mfma_f32_16x16x32_bf16 v[70:73], v[162:165], v[194:197], v[70:73]
	v_mfma_f32_16x16x32_bf16 v[114:117], v[154:157], v[186:189], v[114:117]
	v_mfma_f32_16x16x32_bf16 v[82:85], v[162:165], v[186:189], v[82:85]
	v_mfma_f32_16x16x32_bf16 v[110:113], v[154:157], v[178:181], v[110:113]
	v_mfma_f32_16x16x32_bf16 v[78:81], v[162:165], v[178:181], v[78:81]
	v_mfma_f32_16x16x32_bf16 v[106:109], v[154:157], v[170:173], v[106:109]
	v_mfma_f32_16x16x32_bf16 v[74:77], v[162:165], v[170:173], v[74:77]
	v_mfma_f32_16x16x32_bf16 v[130:133], v[134:137], v[190:193], v[130:133]
	v_mfma_f32_16x16x32_bf16 v[98:101], v[142:145], v[190:193], v[98:101]
	v_mfma_f32_16x16x32_bf16 v[126:129], v[134:137], v[182:185], v[126:129]
	v_mfma_f32_16x16x32_bf16 v[94:97], v[142:145], v[182:185], v[94:97]
	v_mfma_f32_16x16x32_bf16 v[122:125], v[134:137], v[174:177], v[122:125]
	v_mfma_f32_16x16x32_bf16 v[90:93], v[142:145], v[174:177], v[90:93]
	v_mfma_f32_16x16x32_bf16 v[118:121], v[134:137], v[166:169], v[118:121]
	v_mfma_f32_16x16x32_bf16 v[86:89], v[142:145], v[166:169], v[86:89]
	v_mfma_f32_16x16x32_bf16 v[130:133], v[138:141], v[194:197], v[130:133]
	v_mfma_f32_16x16x32_bf16 v[98:101], v[146:149], v[194:197], v[98:101]
	v_mfma_f32_16x16x32_bf16 v[126:129], v[138:141], v[186:189], v[126:129]
	v_mfma_f32_16x16x32_bf16 v[94:97], v[146:149], v[186:189], v[94:97]
	v_mfma_f32_16x16x32_bf16 v[122:125], v[138:141], v[178:181], v[122:125]
	v_mfma_f32_16x16x32_bf16 v[90:93], v[146:149], v[178:181], v[90:93]
	v_mfma_f32_16x16x32_bf16 v[118:121], v[138:141], v[170:173], v[118:121]
	v_mfma_f32_16x16x32_bf16 v[86:89], v[146:149], v[170:173], v[86:89]
	s_setprio 0
	s_barrier
	ds_read_b128 v[190:193], v250 offset:49152
	ds_read_b128 v[194:197], v250 offset:50176
	ds_read_b128 v[182:185], v250 offset:51200
	ds_read_b128 v[186:189], v250 offset:52224
	ds_read_b128 v[174:177], v250 offset:53248
	ds_read_b128 v[178:181], v250 offset:54272
	ds_read_b128 v[166:169], v250 offset:55296
	ds_read_b128 v[170:173], v250 offset:56320
	s_mov_b64 s[84:85], -1
	s_and_b64 vcc, exec, s[88:89]
	s_cbranch_vccz .LBB0_119
	s_waitcnt vmcnt(0)
	s_mov_b64 s[84:85], 0
.LBB0_119:
	s_andn2_b64 vcc, exec, s[84:85]
	s_cbranch_vccnz .LBB0_105
	s_mov_b32 m0, s54
	v_lshl_add_u64 v[224:225], v[224:225], 0, s[12:13]
	s_add_u32 s2, s2, 0x40080
	global_load_lds_dwordx4 v[224:225], off
	v_lshl_add_u64 v[222:223], v[222:223], 0, s[12:13]
	s_mov_b32 m0, s55
	s_addc_u32 s3, s3, 0
	global_load_lds_dwordx4 v[222:223], off
	v_lshl_add_u64 v[222:223], s[2:3], 0, v[208:209]
	s_mov_b32 m0, s59
	v_lshl_add_u64 v[220:221], v[220:221], 0, s[12:13]
	global_load_lds_dwordx4 v[222:223], off
	v_lshl_add_u64 v[222:223], s[2:3], 0, v[212:213]
	s_mov_b32 m0, s24
	v_lshl_add_u64 v[4:5], v[4:5], 0, s[12:13]
	global_load_lds_dwordx4 v[222:223], off
	s_mov_b32 m0, s57
	s_nop 0
	global_load_lds_dwordx4 v[220:221], off
	s_mov_b32 m0, s58
	s_nop 0
	global_load_lds_dwordx4 v[4:5], off
	s_waitcnt vmcnt(8)
	s_branch .LBB0_105
.LBB0_122:
	s_and_b64 vcc, exec, s[14:15]
	s_cbranch_vccz .LBB0_124
	s_barrier
